# prompt attention: selection mask applied with bfe_i32 + bfi (-inf) instead of bfe + lshl_or + min (size-neutral: one s_nop keeps the code placement)
# speedup vs baseline: 1.0106x; 1.0106x over previous
.LBB0_1884:
	v_readlane_b32 s3, v251, 5
	s_and_b32 s33, s3, 3
	s_ashr_i32 s0, s3, 6
	s_xor_b32 s39, s33, 7
	s_add_u32 s44, s6, 0x14a00000
	s_addc_u32 s45, s7, 0
	s_ashr_i32 s1, s0, 31
	s_lshl_b64 s[20:21], s[0:1], 11
	s_lshl_b64 s[0:1], s[0:1], 20
	s_cmp_lg_u32 0, -1
	s_waitcnt vmcnt(0)
	v_lshlrev_b32_e32 v2, 1, v0
	s_cselect_b32 s2, 0, 0
	v_and_b32_e32 v2, 32, v2
	s_addk_i32 s2, 0x6000
	v_add_u32_e32 v11, s2, v2
	s_lshl_b32 s2, s3, 5
	s_and_b32 s46, s3, 0xffffffc0
	s_and_b32 s2, s2, 0x780
	s_add_u32 s47, s54, s2
	s_addc_u32 s48, s55, 0
	v_lshlrev_b32_e32 v6, 4, v0
	s_add_u32 s0, s6, s0
	v_lshrrev_b32_e32 v5, 5, v198
	v_and_b32_e32 v6, 0xc0, v6
	s_addc_u32 s1, s7, s1
	s_lshl_b32 s2, s3, 3
	v_lshlrev_b32_e32 v9, 3, v0
	v_lshl_or_b32 v13, v5, 8, v6
	v_lshlrev_b32_e32 v14, 10, v5
	v_lshlrev_b32_e32 v15, 4, v100
	s_and_b32 s2, s2, 0x180
	v_lshlrev_b32_e32 v12, 3, v5
	v_lshlrev_b32_e32 v237, 4, v5
	v_lshlrev_b32_e32 v238, 9, v5
	v_lshrrev_b32_e32 v5, 3, v198
	v_and_b32_e32 v4, 24, v9
	s_add_u32 s0, s0, s2
	v_add3_u32 v235, 0, v14, v15
	v_and_b32_e32 v14, 56, v9
	v_or_b32_e32 v9, 8, v5
	s_addc_u32 s1, s1, 0
	v_lshlrev_b32_e32 v239, 7, v5
	v_lshlrev_b32_e32 v16, 10, v5
	v_lshlrev_b32_e32 v240, 7, v9
	v_lshlrev_b32_e32 v18, 10, v9
	v_or_b32_e32 v9, 16, v5
	v_or_b32_e32 v5, 24, v5
	v_mov_b32_e32 v3, 0
	v_add_u32_e32 v8, 0, v2
	s_add_u32 s24, s0, 0xac00000
	v_lshlrev_b32_e32 v2, 9, v198
	v_lshlrev_b32_e32 v242, 7, v5
	v_lshlrev_b32_e32 v22, 10, v5
	v_lshlrev_b32_e32 v5, 2, v0
	s_addc_u32 s25, s1, 0
	v_lshl_add_u64 v[6:7], s[0:1], 0, v[2:3]
	s_mov_b64 s[0:1], 0xa700000
	v_and_b32_e32 v5, 0x80, v5
	v_lshlrev_b32_e32 v243, 2, v100
	v_lshl_add_u64 v[200:201], v[6:7], 0, s[0:1]
	v_add3_u32 v199, v8, v4, v13
	v_and_b32_e32 v7, 32, v0
	v_or_b32_e32 v2, 0x100, v198
	v_or_b32_e32 v6, 0x140, v198
	v_or_b32_e32 v8, 0x180, v198
	v_or_b32_e32 v10, 0x1c0, v198
	v_lshlrev_b32_e32 v20, 10, v9
	v_add3_u32 v5, v5, v243, 0
	v_lshrrev_b32_e32 v101, 2, v198
	s_mov_b32 s23, 0
	v_or_b32_e32 v228, 0x400, v1
	v_or_b32_e32 v229, 0x800, v1
	v_or_b32_e32 v230, 0xc00, v1
	v_lshlrev_b32_e32 v231, 4, v2
	v_lshlrev_b32_e32 v232, 4, v6
	v_lshlrev_b32_e32 v233, 4, v8
	v_lshlrev_b32_e32 v234, 4, v10
	v_lshlrev_b32_e32 v202, 11, v100
	v_mov_b32_e32 v203, v3
	v_add3_u32 v236, v11, v4, v13
	v_cmp_gt_u32_e64 s[0:1], 32, v198
	v_lshlrev_b32_e32 v241, 7, v9
	v_add_u32_e32 v244, 0x15100, v5
	s_mov_b64 s[2:3], -1
	v_lshlrev_b32_e32 v204, 4, v198
	v_lshlrev_b32_e32 v245, 4, v2
	v_lshlrev_b32_e32 v246, 4, v6
	v_lshlrev_b32_e32 v247, 4, v8
	v_lshlrev_b32_e32 v248, 4, v10
	v_lshlrev_b32_e32 v249, 2, v7
	s_mov_b64 s[26:27], 0x8000
	s_mov_b64 s[28:29], 0x10000
	s_mov_b32 s49, 0xff800000
	s_mov_b32 s50, 0xff61b1e6
	s_mov_b64 s[30:31], 0x18000
	s_mov_b64 s[34:35], 0x20000
	s_mov_b32 s51, 0x41000000
	s_mov_b64 s[36:37], 0x28000
	v_lshlrev_b32_e32 v206, 1, v14
	v_lshlrev_b32_e32 v208, 1, v16
	v_lshlrev_b32_e32 v210, 1, v18
	v_lshlrev_b32_e32 v212, 1, v20
	v_lshlrev_b32_e32 v214, 1, v22
	v_mov_b32_e32 v205, v3
	v_lshlrev_b32_e32 v216, 1, v4
	v_lshlrev_b32_e32 v218, 1, v12
	s_branch .LBB0_1886

.LBB0_1900:
	s_lshl_b32 s56, s8, 8
	s_or_b32 s4, s20, s56
	s_lshl_b32 s5, s52, 5
	s_add_u32 s4, s4, s5
	s_addc_u32 s5, s21, 0
	s_and_b32 s53, s7, 0x3fffffc0
	s_lshl_b32 s22, s52, 4
	s_lshl_b32 s57, s52, 10
	s_cmp_lg_u32 0, -1
	s_cselect_b32 s8, 0, 0
	s_add_i32 s57, s57, s8
	s_add_i32 s59, s56, 0x100
	s_lshl_b64 s[4:5], s[4:5], 11
	v_and_or_b32 v2, s22, 48, v101
	s_add_u32 s40, s47, s4
	s_addc_u32 s41, s48, s5
	v_lshlrev_b32_e32 v2, 9, v2
	s_lshr_b32 s4, s7, 2
	v_lshl_add_u64 v[220:221], v[200:201], 0, s[22:23]
	v_lshl_add_u64 v[4:5], s[24:25], 0, v[2:3]
	s_and_b32 s22, s4, 0x3fffffc0
	s_waitcnt vmcnt(0) lgkmcnt(0)
	v_lshl_add_u64 v[4:5], v[4:5], 0, s[22:23]
	v_mov_b32_e32 v217, v3
	s_mov_b32 s4, m0
	s_mov_b32 m0, s57
	s_nop 0
	global_load_lds_dwordx4 v[220:221], off
	s_mov_b32 m0, s4
	v_lshl_add_u64 v[222:223], v[4:5], 0, v[216:217]
	s_add_i32 s58, s57, 0x6000
	s_mov_b32 s4, m0
	s_mov_b32 m0, s58
	s_nop 0
	global_load_lds_dwordx4 v[222:223], off
	s_mov_b32 m0, s4
	v_lshl_add_u64 v[4:5], v[220:221], 0, s[26:27]
	s_add_i32 s4, s57, 0x2000
	s_mov_b32 s5, m0
	s_mov_b32 m0, s4
	s_nop 0
	global_load_lds_dwordx4 v[4:5], off
	s_mov_b32 m0, s5
	v_lshl_add_u64 v[4:5], s[40:41], 0, v[202:203]
	v_mov_b32_e32 v219, v3
	v_lshl_add_u64 v[4:5], v[4:5], 0, v[218:219]
	global_load_dwordx4 v[130:133], v[4:5], off
	global_load_dwordx4 v[126:129], v[4:5], off offset:32
	global_load_dwordx4 v[122:125], v[4:5], off offset:64
	global_load_dwordx4 v[114:117], v[4:5], off offset:96
	v_lshl_add_u64 v[4:5], v[220:221], 0, s[28:29]
	s_add_i32 s4, s57, 0x4000
	s_mov_b32 s5, m0
	s_mov_b32 m0, s4
	s_nop 0
	global_load_lds_dwordx4 v[4:5], off
	s_mov_b32 m0, s5
	s_waitcnt vmcnt(3) lgkmcnt(0)
	s_barrier
	ds_read_b128 v[4:7], v235
	ds_read_b128 v[20:23], v235 offset:512
	ds_read_b128 v[36:39], v235 offset:2048
	v_add3_u32 v209, s6, v249, v243
	s_lshl_b32 s22, s53, 2
	s_add_i32 s53, s22, 0
	s_mov_b32 s4, 0
	s_movk_i32 s60, 0x2000
	s_movk_i32 s62, 0x4000
	s_lshr_b32 s59, s59, 6
	s_mov_b32 s22, 1
	v_lshl_add_u32 v207, v100, 2, s53
	s_waitcnt vmcnt(3) lgkmcnt(2)
	v_mfma_f32_32x32x16_bf16 v[4:19], v[4:7], v[130:133], 0
	s_waitcnt vmcnt(2) lgkmcnt(0)
	v_mfma_f32_32x32x16_bf16 v[4:19], v[36:39], v[126:129], v[4:19]
	ds_read_b128 v[36:39], v235 offset:2560
	v_mfma_f32_32x32x16_bf16 v[20:35], v[20:23], v[130:133], 0
	s_waitcnt lgkmcnt(0)
	v_mfma_f32_32x32x16_bf16 v[20:35], v[36:39], v[126:129], v[20:35]
	ds_read_b128 v[36:39], v235 offset:4096
	ds_read_b128 v[40:43], v235 offset:4608
	s_waitcnt vmcnt(1) lgkmcnt(1)
	v_mfma_f32_32x32x16_bf16 v[4:19], v[36:39], v[122:125], v[4:19]
	ds_read_b128 v[36:39], v235 offset:6656
	ds_read_b128 v[44:47], v235 offset:6144
	s_waitcnt lgkmcnt(2)
	v_mfma_f32_32x32x16_bf16 v[20:35], v[40:43], v[122:125], v[20:35]
	s_waitcnt vmcnt(0) lgkmcnt(0)
	v_mfma_f32_32x32x16_bf16 v[4:19], v[44:47], v[114:117], v[4:19]
	v_mfma_f32_32x32x16_bf16 v[20:35], v[36:39], v[114:117], v[20:35]
	s_nop 15
	s_nop 7
	ds_read_b32 v2, v209
	s_waitcnt lgkmcnt(0)
	v_bfe_i32 v36, v2, 0, 1
	v_bfi_b32 v4, v36, s49, v4
	s_nop 0
	s_waitcnt vmcnt(0) lgkmcnt(0)
	s_barrier
	s_nop 0
	v_bfe_i32 v36, v2, 1, 1
	v_bfi_b32 v5, v36, s49, v5
	s_nop 0
	s_nop 0
	v_bfe_i32 v36, v2, 2, 1
	v_bfi_b32 v6, v36, s49, v6
	s_nop 0
	s_nop 0
	v_bfe_i32 v36, v2, 3, 1
	v_bfi_b32 v7, v36, s49, v7
	s_nop 0
	s_nop 0
	v_bfe_i32 v36, v2, 4, 1
	v_bfi_b32 v8, v36, s49, v8
	s_nop 0
	s_nop 0
	v_bfe_i32 v36, v2, 5, 1
	v_bfi_b32 v9, v36, s49, v9
	s_nop 0
	s_nop 0
	v_bfe_i32 v36, v2, 6, 1
	v_bfi_b32 v10, v36, s49, v10
	s_nop 0
	s_nop 0
	v_bfe_i32 v36, v2, 7, 1
	v_bfi_b32 v11, v36, s49, v11
	s_nop 0
	s_nop 0
	v_bfe_i32 v36, v2, 8, 1
	v_bfi_b32 v12, v36, s49, v12
	s_nop 0
	s_nop 0
	v_bfe_i32 v36, v2, 9, 1
	v_bfi_b32 v13, v36, s49, v13
	s_nop 0
	s_nop 0
	v_bfe_i32 v36, v2, 10, 1
	v_bfi_b32 v14, v36, s49, v14
	s_nop 0
	s_nop 0
	v_bfe_i32 v36, v2, 11, 1
	v_bfi_b32 v15, v36, s49, v15
	s_nop 0
	s_nop 0
	v_bfe_i32 v36, v2, 12, 1
	v_bfi_b32 v16, v36, s49, v16
	s_nop 0
	s_nop 0
	v_bfe_i32 v36, v2, 13, 1
	v_bfi_b32 v17, v36, s49, v17
	s_nop 0
	s_nop 0
	v_bfe_i32 v36, v2, 14, 1
	v_bfi_b32 v18, v36, s49, v18
	s_nop 0
	s_nop 0
	v_bfe_i32 v36, v2, 15, 1
	v_bfi_b32 v19, v36, s49, v19
	s_nop 0
	s_nop 0
	v_bfe_i32 v36, v2, 16, 1
	v_bfi_b32 v20, v36, s49, v20
	s_nop 0
	s_nop 0
	v_bfe_i32 v36, v2, 17, 1
	v_bfi_b32 v21, v36, s49, v21
	s_nop 0
	s_nop 0
	v_bfe_i32 v36, v2, 18, 1
	v_bfi_b32 v22, v36, s49, v22
	s_nop 0
	s_nop 0
	v_bfe_i32 v36, v2, 19, 1
	v_bfi_b32 v23, v36, s49, v23
	s_nop 0
	s_nop 0
	v_bfe_i32 v36, v2, 20, 1
	v_bfi_b32 v24, v36, s49, v24
	s_nop 0
	s_nop 0
	v_bfe_i32 v36, v2, 21, 1
	v_bfi_b32 v25, v36, s49, v25
	s_nop 0
	s_nop 0
	v_bfe_i32 v36, v2, 22, 1
	v_bfi_b32 v26, v36, s49, v26
	s_nop 0
	s_nop 0
	v_bfe_i32 v36, v2, 23, 1
	v_bfi_b32 v27, v36, s49, v27
	s_nop 0
	s_nop 0
	v_bfe_i32 v36, v2, 24, 1
	v_bfi_b32 v28, v36, s49, v28
	s_nop 0
	s_nop 0
	v_bfe_i32 v36, v2, 25, 1
	v_bfi_b32 v29, v36, s49, v29
	s_nop 0
	s_nop 0
	v_bfe_i32 v36, v2, 26, 1
	v_bfi_b32 v30, v36, s49, v30
	s_nop 0
	s_nop 0
	v_bfe_i32 v36, v2, 27, 1
	v_bfi_b32 v31, v36, s49, v31
	s_nop 0
	s_nop 0
	v_bfe_i32 v36, v2, 28, 1
	v_bfi_b32 v32, v36, s49, v32
	s_nop 0
	s_nop 0
	v_bfe_i32 v36, v2, 29, 1
	v_bfi_b32 v33, v36, s49, v33
	s_nop 0
	s_nop 0
	v_bfe_i32 v36, v2, 30, 1
	v_bfi_b32 v34, v36, s49, v34
	s_nop 0
	s_nop 0
	v_bfe_i32 v36, v2, 31, 1
	v_bfi_b32 v35, v36, s49, v35
	s_nop 0
	v_max3_f32 v2, v4, v5, v20
	s_nop 0
	v_max3_f32 v36, v6, v7, v21
	v_max3_f32 v2, v2, v22, v23
	s_nop 0
	v_max3_f32 v36, v36, v10, v11
	v_max3_f32 v2, v2, v8, v9
	s_nop 0
	v_max3_f32 v36, v36, v26, v27
	v_max3_f32 v2, v2, v24, v25
	s_nop 0
	v_max3_f32 v36, v36, v14, v15
	v_max3_f32 v2, v2, v12, v13
	s_nop 0
	v_max3_f32 v36, v36, v30, v31
	v_max3_f32 v2, v2, v28, v29
	s_nop 0
	v_max3_f32 v36, v36, v18, v19
	v_max3_f32 v2, v2, v16, v17
	s_nop 0
	v_max3_f32 v36, v36, v34, v35
	v_max3_f32 v2, v2, v32, v33
	s_nop 0
	v_max_f32_e32 v2, v2, v36
	s_nop 0
	v_mov_b32_e32 v36, v2
	s_nop 1
	v_permlane32_swap_b32_e32 v2, v36
	v_max_f32_e32 v2, v2, v36
	s_nop 0
	v_cmp_ngt_f32_e32 vcc, s50, v2
	s_nop 1
	v_cndmask_b32_e32 v2, 0, v2, vcc
	v_sub_f32_e32 v4, v4, v2
	v_sub_f32_e32 v5, v5, v2
	v_add_f32_e32 v211, v3, v2
	v_sub_f32_e32 v20, v20, v2
	v_sub_f32_e32 v21, v21, v2
	v_sub_f32_e32 v6, v6, v2
	s_nop 0
	v_exp_f32_e32 v52, v4
	v_exp_f32_e32 v53, v5
	v_lshl_add_u64 v[4:5], v[220:221], 0, s[30:31]
	s_mov_b32 s63, m0
	s_mov_b32 m0, s57
	s_nop 0
	global_load_lds_dwordx4 v[4:5], off
	s_mov_b32 m0, s63
	v_lshl_add_u64 v[4:5], v[222:223], 0, s[26:27]
	s_add_i32 s63, s57, 0x8000
	s_mov_b32 s64, m0
	s_mov_b32 m0, s63
	s_nop 0
	global_load_lds_dwordx4 v[4:5], off
	s_mov_b32 m0, s64
	ds_read_b128 v[162:165], v235 offset:8192
	ds_read_b128 v[158:161], v235 offset:8704
	ds_read_b128 v[154:157], v235 offset:10240
	ds_read_b128 v[150:153], v235 offset:10752
	ds_read_b128 v[146:149], v235 offset:12288
	ds_read_b128 v[142:145], v235 offset:12800
	ds_read_b128 v[138:141], v235 offset:14336
	ds_read_b128 v[134:137], v235 offset:14848
	v_sub_f32_e32 v22, v22, v2
	v_sub_f32_e32 v7, v7, v2
	v_sub_f32_e32 v23, v23, v2
	v_sub_f32_e32 v8, v8, v2
	v_sub_f32_e32 v24, v24, v2
	v_sub_f32_e32 v9, v9, v2
	v_sub_f32_e32 v25, v25, v2
	v_sub_f32_e32 v10, v10, v2
	v_sub_f32_e32 v26, v26, v2
	v_sub_f32_e32 v11, v11, v2
	v_sub_f32_e32 v27, v27, v2
	v_sub_f32_e32 v12, v12, v2
	v_sub_f32_e32 v28, v28, v2
	v_sub_f32_e32 v13, v13, v2
	v_sub_f32_e32 v29, v29, v2
	v_sub_f32_e32 v14, v14, v2
	v_sub_f32_e32 v30, v30, v2
	v_sub_f32_e32 v15, v15, v2
	v_sub_f32_e32 v31, v31, v2
	v_sub_f32_e32 v16, v16, v2
	v_sub_f32_e32 v32, v32, v2
	v_sub_f32_e32 v17, v17, v2
	v_sub_f32_e32 v33, v33, v2
	v_sub_f32_e32 v18, v18, v2
	v_sub_f32_e32 v34, v34, v2
	v_sub_f32_e32 v19, v19, v2
	v_sub_f32_e32 v2, v35, v2
	v_exp_f32_e32 v54, v6
	v_exp_f32_e32 v55, v7
	v_exp_f32_e32 v56, v8
	v_exp_f32_e32 v57, v9
	v_exp_f32_e32 v58, v10
	v_exp_f32_e32 v59, v11
	v_exp_f32_e32 v60, v12
	v_exp_f32_e32 v61, v13
	v_exp_f32_e32 v62, v14
	v_exp_f32_e32 v63, v15
	v_exp_f32_e32 v64, v16
	v_exp_f32_e32 v65, v17
	v_exp_f32_e32 v66, v18
	v_exp_f32_e32 v67, v19
	v_exp_f32_e32 v36, v20
	v_exp_f32_e32 v37, v21
	v_exp_f32_e32 v38, v22
	v_exp_f32_e32 v39, v23
	v_exp_f32_e32 v40, v24
	v_exp_f32_e32 v41, v25
	v_exp_f32_e32 v42, v26
	v_exp_f32_e32 v43, v27
	v_exp_f32_e32 v44, v28
	v_exp_f32_e32 v45, v29
	v_exp_f32_e32 v46, v30
	v_exp_f32_e32 v47, v31
	v_exp_f32_e32 v48, v32
	v_exp_f32_e32 v49, v33
	v_exp_f32_e32 v50, v34
	v_exp_f32_e32 v51, v2
	s_waitcnt vmcnt(2) lgkmcnt(0)
	s_barrier
	s_andn2_b64 vcc, exec, s[42:43]
	s_cbranch_vccnz .LBB0_1962
	v_mov_b32_e32 v16, v3
	v_mov_b32_e32 v17, v3
	v_mov_b32_e32 v2, v3
	v_mov_b32_e32 v4, v3
	v_mov_b32_e32 v5, v3
	v_mov_b32_e32 v6, v3
	v_mov_b32_e32 v7, v3
	v_mov_b32_e32 v8, v3
	v_mov_b32_e32 v9, v3
	v_mov_b32_e32 v10, v3
	v_mov_b32_e32 v11, v3
	v_mov_b32_e32 v12, v3
	v_mov_b32_e32 v13, v3
	v_mov_b32_e32 v14, v3
	v_mov_b32_e32 v15, v3
	v_mov_b64_e32 v[34:35], v[16:17]
	v_mov_b64_e32 v[32:33], v[14:15]
	v_mov_b64_e32 v[30:31], v[12:13]
	v_mov_b64_e32 v[28:29], v[10:11]
	v_mov_b64_e32 v[26:27], v[8:9]
	v_mov_b64_e32 v[24:25], v[6:7]
	v_mov_b64_e32 v[22:23], v[4:5]
	v_mov_b64_e32 v[20:21], v[2:3]
	v_mov_b64_e32 v[18:19], v[16:17]
	v_add_u32_e32 v182, s61, v244
	s_mov_b32 s8, 0
	s_movk_i32 s4, 0x4000
	s_movk_i32 s12, 0x2000
	v_mov_b32_e32 v213, 0
	s_mov_b32 s5, 6
	s_mov_b64 s[6:7], 0
	v_mov_b64_e32 v[16:17], v[14:15]
	v_mov_b64_e32 v[14:15], v[12:13]
	v_mov_b64_e32 v[12:13], v[10:11]
	v_mov_b64_e32 v[10:11], v[8:9]
	v_mov_b64_e32 v[8:9], v[6:7]
	v_mov_b64_e32 v[6:7], v[4:5]
	v_mov_b64_e32 v[4:5], v[2:3]
.LBB0_1902:
	v_add_u32_e32 v2, s8, v199
	ds_read_b64_tr_b16 v[166:167], v2 offset:24576
	ds_read_b64_tr_b16 v[168:169], v2 offset:25088
	v_add_f32_e32 v68, v52, v53
	v_add_f32_e32 v68, v54, v68
	v_add_f32_e32 v68, v55, v68
	v_add_f32_e32 v68, v56, v68
	v_add_f32_e32 v84, v57, v68
	s_waitcnt lgkmcnt(9)
	v_mfma_f32_32x32x16_bf16 v[68:83], v[162:165], v[130:133], 0
	v_cvt_pk_bf16_f32 v118, v52, v53
	v_cvt_pk_bf16_f32 v119, v54, v55
	ds_read_b64_tr_b16 v[162:163], v2 offset:28672
	ds_read_b64_tr_b16 v[164:165], v2 offset:29184
	v_add_f32_e32 v52, v58, v84
	v_add_f32_e32 v52, v59, v52
	v_add_f32_e32 v52, v60, v52
	v_add_f32_e32 v52, v61, v52
	v_cvt_pk_bf16_f32 v120, v56, v57
	v_cvt_pk_bf16_f32 v121, v58, v59
	s_waitcnt lgkmcnt(10)
	v_mfma_f32_32x32x16_bf16 v[84:99], v[158:161], v[130:133], 0
	ds_read_b64_tr_b16 v[158:159], v2 offset:25600
	ds_read_b64_tr_b16 v[160:161], v2 offset:26112
	s_waitcnt lgkmcnt(11)
	v_mfma_f32_32x32x16_bf16 v[68:83], v[154:157], v[126:129], v[68:83]
	v_add_f32_e32 v52, v62, v52
	v_add_f32_e32 v52, v63, v52
	v_add_f32_e32 v52, v64, v52
	v_add_f32_e32 v52, v65, v52
	v_cvt_pk_bf16_f32 v110, v60, v61
	v_cvt_pk_bf16_f32 v111, v62, v63
	ds_read_b64_tr_b16 v[154:155], v2 offset:29696
	ds_read_b64_tr_b16 v[156:157], v2 offset:30208
	v_add_f32_e32 v52, v66, v52
	v_add_f32_e32 v52, v67, v52
	v_add_f32_e32 v52, v36, v52
	v_add_f32_e32 v52, v37, v52
	v_cvt_pk_bf16_f32 v112, v64, v65
	v_cvt_pk_bf16_f32 v113, v66, v67
	s_waitcnt lgkmcnt(12)
	v_mfma_f32_32x32x16_bf16 v[84:99], v[150:153], v[126:129], v[84:99]
	ds_read_b64_tr_b16 v[150:151], v2 offset:26624
	ds_read_b64_tr_b16 v[152:153], v2 offset:27136
	s_waitcnt lgkmcnt(13)
	v_mfma_f32_32x32x16_bf16 v[68:83], v[146:149], v[122:125], v[68:83]
	v_add_f32_e32 v52, v38, v52
	v_add_f32_e32 v52, v39, v52
	v_add_f32_e32 v52, v40, v52
	v_add_f32_e32 v52, v41, v52
	v_cvt_pk_bf16_f32 v106, v36, v37
	v_cvt_pk_bf16_f32 v107, v38, v39
	ds_read_b64_tr_b16 v[146:147], v2 offset:30720
	ds_read_b64_tr_b16 v[148:149], v2 offset:31232
	v_add_f32_e32 v36, v42, v52
	v_add_f32_e32 v36, v43, v36
	v_add_f32_e32 v36, v44, v36
	v_add_f32_e32 v36, v45, v36
	v_cvt_pk_bf16_f32 v108, v40, v41
	v_cvt_pk_bf16_f32 v109, v42, v43
	s_waitcnt lgkmcnt(14)
	v_mfma_f32_32x32x16_bf16 v[84:99], v[142:145], v[122:125], v[84:99]
	ds_read_b64_tr_b16 v[142:143], v2 offset:27648
	ds_read_b64_tr_b16 v[144:145], v2 offset:28160
	s_waitcnt lgkmcnt(14)
	v_mfma_f32_32x32x16_bf16 v[68:83], v[138:141], v[114:117], v[68:83]
	v_add_f32_e32 v36, v46, v36
	v_add_f32_e32 v36, v47, v36
	v_add_f32_e32 v36, v48, v36
	v_add_f32_e32 v36, v49, v36
	v_cvt_pk_bf16_f32 v102, v44, v45
	v_cvt_pk_bf16_f32 v103, v46, v47
	ds_read_b64_tr_b16 v[138:139], v2 offset:31744
	ds_read_b64_tr_b16 v[140:141], v2 offset:32256
	v_add_f32_e32 v2, v50, v36
	v_add_f32_e32 v2, v51, v2
	v_add_f32_e32 v2, 0, v2
	v_cvt_pk_bf16_f32 v104, v48, v49
	v_cvt_pk_bf16_f32 v105, v50, v51
	v_mfma_f32_32x32x16_bf16 v[84:99], v[134:137], v[114:117], v[84:99]
	v_lshl_add_u64 v[178:179], v[220:221], 0, s[6:7]
	v_lshl_add_u64 v[36:37], v[178:179], 0, s[34:35]
	v_lshl_add_u64 v[180:181], v[222:223], 0, s[6:7]
	s_add_i32 s8, s12, s57
	s_mov_b32 s9, m0
	s_mov_b32 m0, s8
	s_nop 0
	global_load_lds_dwordx4 v[36:37], off
	s_mov_b32 m0, s9
	v_lshl_add_u64 v[36:37], v[180:181], 0, s[28:29]
	s_add_i32 s8, s4, s58
	s_mov_b32 s9, m0
	s_mov_b32 m0, s8
	s_nop 0
	global_load_lds_dwordx4 v[36:37], off
	s_mov_b32 m0, s9
	v_sub_f32_e32 v52, v68, v211
	s_nop 4
	v_sub_f32_e32 v36, v84, v211
	v_sub_f32_e32 v53, v69, v211
	v_sub_f32_e32 v37, v85, v211
	v_sub_f32_e32 v54, v70, v211
	v_sub_f32_e32 v38, v86, v211
	v_sub_f32_e32 v55, v71, v211
	v_sub_f32_e32 v39, v87, v211
	v_sub_f32_e32 v56, v72, v211
	v_sub_f32_e32 v40, v88, v211
	v_sub_f32_e32 v57, v73, v211
	v_sub_f32_e32 v41, v89, v211
	v_sub_f32_e32 v58, v74, v211
	v_sub_f32_e32 v42, v90, v211
	v_sub_f32_e32 v59, v75, v211
	v_sub_f32_e32 v43, v91, v211
	v_sub_f32_e32 v60, v76, v211
	v_sub_f32_e32 v44, v92, v211
	v_sub_f32_e32 v61, v77, v211
	v_sub_f32_e32 v45, v93, v211
	v_sub_f32_e32 v62, v78, v211
	v_sub_f32_e32 v46, v94, v211
	v_sub_f32_e32 v63, v79, v211
	v_sub_f32_e32 v47, v95, v211
	v_sub_f32_e32 v64, v80, v211
	v_sub_f32_e32 v48, v96, v211
	v_sub_f32_e32 v65, v81, v211
	v_sub_f32_e32 v49, v97, v211
	v_sub_f32_e32 v66, v82, v211
	v_sub_f32_e32 v50, v98, v211
	v_sub_f32_e32 v67, v83, v211
	v_sub_f32_e32 v51, v99, v211
	ds_read_b32 v68, v182
	s_waitcnt lgkmcnt(0)
	v_bfe_i32 v69, v68, 0, 1
	v_bfi_b32 v52, v69, s49, v52
	s_nop 0
	v_add_f32_e32 v2, v213, v2
	v_bfe_i32 v69, v68, 1, 1
	v_bfi_b32 v53, v69, s49, v53
	s_nop 0
	s_nop 0
	v_bfe_i32 v69, v68, 2, 1
	v_bfi_b32 v54, v69, s49, v54
	s_nop 0
	s_nop 0
	v_bfe_i32 v69, v68, 3, 1
	v_bfi_b32 v55, v69, s49, v55
	s_nop 0
	s_nop 0
	v_bfe_i32 v69, v68, 4, 1
	v_bfi_b32 v56, v69, s49, v56
	s_nop 0
	s_nop 0
	v_bfe_i32 v69, v68, 5, 1
	v_bfi_b32 v57, v69, s49, v57
	s_nop 0
	s_nop 0
	v_bfe_i32 v69, v68, 6, 1
	v_bfi_b32 v58, v69, s49, v58
	s_nop 0
	s_nop 0
	v_bfe_i32 v69, v68, 7, 1
	v_bfi_b32 v59, v69, s49, v59
	s_nop 0
	s_nop 0
	v_bfe_i32 v69, v68, 8, 1
	v_bfi_b32 v60, v69, s49, v60
	s_nop 0
	s_nop 0
	v_bfe_i32 v69, v68, 9, 1
	v_bfi_b32 v61, v69, s49, v61
	s_nop 0
	s_nop 0
	v_bfe_i32 v69, v68, 10, 1
	v_bfi_b32 v62, v69, s49, v62
	s_nop 0
	s_nop 0
	v_bfe_i32 v69, v68, 11, 1
	v_bfi_b32 v63, v69, s49, v63
	s_nop 0
	s_nop 0
	v_bfe_i32 v69, v68, 12, 1
	v_bfi_b32 v64, v69, s49, v64
	s_nop 0
	s_nop 0
	v_bfe_i32 v69, v68, 13, 1
	v_bfi_b32 v65, v69, s49, v65
	s_nop 0
	s_nop 0
	v_bfe_i32 v69, v68, 14, 1
	v_bfi_b32 v66, v69, s49, v66
	s_nop 0
	s_nop 0
	v_bfe_i32 v69, v68, 15, 1
	v_bfi_b32 v67, v69, s49, v67
	s_nop 0
	s_nop 0
	v_bfe_i32 v69, v68, 16, 1
	v_bfi_b32 v36, v69, s49, v36
	s_nop 0
	s_nop 0
	v_bfe_i32 v69, v68, 17, 1
	v_bfi_b32 v37, v69, s49, v37
	s_nop 0
	s_nop 0
	v_bfe_i32 v69, v68, 18, 1
	v_bfi_b32 v38, v69, s49, v38
	s_nop 0
	s_nop 0
	v_bfe_i32 v69, v68, 19, 1
	v_bfi_b32 v39, v69, s49, v39
	s_nop 0
	s_nop 0
	v_bfe_i32 v69, v68, 20, 1
	v_bfi_b32 v40, v69, s49, v40
	s_nop 0
	s_nop 0
	v_bfe_i32 v69, v68, 21, 1
	v_bfi_b32 v41, v69, s49, v41
	s_nop 0
	s_nop 0
	v_bfe_i32 v69, v68, 22, 1
	v_bfi_b32 v42, v69, s49, v42
	s_nop 0
	s_nop 0
	v_bfe_i32 v69, v68, 23, 1
	v_bfi_b32 v43, v69, s49, v43
	s_nop 0
	s_nop 0
	v_bfe_i32 v69, v68, 24, 1
	v_bfi_b32 v44, v69, s49, v44
	s_nop 0
	s_nop 0
	v_bfe_i32 v69, v68, 25, 1
	v_bfi_b32 v45, v69, s49, v45
	s_nop 0
	s_nop 0
	v_bfe_i32 v69, v68, 26, 1
	v_bfi_b32 v46, v69, s49, v46
	s_nop 0
	s_nop 0
	v_bfe_i32 v69, v68, 27, 1
	v_bfi_b32 v47, v69, s49, v47
	s_nop 0
	s_nop 0
	v_bfe_i32 v69, v68, 28, 1
	v_bfi_b32 v48, v69, s49, v48
	s_nop 0
	s_nop 0
	v_bfe_i32 v69, v68, 29, 1
	v_bfi_b32 v49, v69, s49, v49
	s_nop 0
	s_nop 0
	v_bfe_i32 v69, v68, 30, 1
	v_bfi_b32 v50, v69, s49, v50
	s_nop 0
	s_nop 0
	v_bfe_i32 v69, v68, 31, 1
	v_bfi_b32 v51, v69, s49, v51
	s_nop 0
	v_max_f32_e32 v68, v53, v53
	v_max_f32_e32 v69, v52, v52
	v_max_f32_e32 v68, v69, v68
	v_max3_f32 v69, v54, v55, v37
	v_max3_f32 v68, v68, v36, v38
	v_max3_f32 v68, v68, v39, v56
	v_max3_f32 v69, v69, v58, v59
	v_max3_f32 v68, v68, v57, v40
	v_max3_f32 v69, v69, v42, v43
	v_max3_f32 v68, v68, v41, v60
	v_max3_f32 v69, v69, v62, v63
	v_max3_f32 v68, v68, v61, v44
	v_max3_f32 v69, v69, v46, v47
	v_max3_f32 v68, v68, v45, v64
	v_max3_f32 v69, v69, v66, v67
	v_max3_f32 v68, v68, v65, v48
	v_max3_f32 v69, v69, v50, v51
	v_max3_f32 v68, v68, v49, v69
	v_mov_b32_e32 v69, v68
	s_nop 1
	v_permlane32_swap_b32_e32 v68, v69
	v_max_f32_e32 v69, v69, v69
	v_max_f32_e32 v68, v68, v68
	v_max_f32_e32 v68, v68, v69
	v_cmp_lt_f32_e32 vcc, s51, v68
	s_cmp_lg_u64 vcc, 0
	s_cselect_b64 s[8:9], -1, 0
	s_cbranch_vccnz .LBB0_1910

.LBB0_1905:
	s_add_i32 s8, s4, 0x2000
	s_cmpk_lg_i32 s4, 0x4000
	s_cselect_b32 s60, s8, 0
	v_add_u32_e32 v183, s12, v199
	ds_read_b64_tr_b16 v[150:151], v183 offset:24576
	ds_read_b64_tr_b16 v[152:153], v183 offset:25088
	v_add_f32_e32 v72, v52, v53
	v_add_f32_e32 v72, v54, v72
	v_add_f32_e32 v72, v55, v72
	v_add_f32_e32 v72, v56, v72
	v_add_f32_e32 v88, v57, v72
	v_cvt_pk_bf16_f32 v118, v52, v53
	v_cvt_pk_bf16_f32 v119, v54, v55
	s_waitcnt lgkmcnt(9)
	v_mfma_f32_32x32x16_bf16 v[68:83], v[68:71], v[130:133], 0
	ds_read_b64_tr_b16 v[146:147], v183 offset:28672
	ds_read_b64_tr_b16 v[148:149], v183 offset:29184
	v_add_f32_e32 v52, v58, v88
	v_add_f32_e32 v52, v59, v52
	v_add_f32_e32 v52, v60, v52
	v_add_f32_e32 v52, v61, v52
	v_cvt_pk_bf16_f32 v120, v56, v57
	v_cvt_pk_bf16_f32 v121, v58, v59
	s_waitcnt lgkmcnt(10)
	v_mfma_f32_32x32x16_bf16 v[84:99], v[84:87], v[130:133], 0
	ds_read_b64_tr_b16 v[142:143], v183 offset:25600
	ds_read_b64_tr_b16 v[144:145], v183 offset:26112
	v_add_f32_e32 v52, v62, v52
	v_add_f32_e32 v52, v63, v52
	v_add_f32_e32 v52, v64, v52
	v_add_f32_e32 v52, v65, v52
	v_cvt_pk_bf16_f32 v110, v60, v61
	v_cvt_pk_bf16_f32 v111, v62, v63
	s_waitcnt lgkmcnt(11)
	v_mfma_f32_32x32x16_bf16 v[68:83], v[170:173], v[126:129], v[68:83]
	ds_read_b64_tr_b16 v[138:139], v183 offset:29696
	ds_read_b64_tr_b16 v[140:141], v183 offset:30208
	v_add_f32_e32 v52, v66, v52
	v_add_f32_e32 v52, v67, v52
	v_add_f32_e32 v52, v36, v52
	v_add_f32_e32 v52, v37, v52
	v_cvt_pk_bf16_f32 v112, v64, v65
	v_cvt_pk_bf16_f32 v113, v66, v67
	s_waitcnt lgkmcnt(12)
	v_mfma_f32_32x32x16_bf16 v[84:99], v[134:137], v[126:129], v[84:99]
	ds_read_b64_tr_b16 v[134:135], v183 offset:26624
	ds_read_b64_tr_b16 v[136:137], v183 offset:27136
	v_add_f32_e32 v52, v38, v52
	v_add_f32_e32 v52, v39, v52
	v_add_f32_e32 v52, v40, v52
	v_add_f32_e32 v52, v41, v52
	v_cvt_pk_bf16_f32 v106, v36, v37
	v_cvt_pk_bf16_f32 v107, v38, v39
	s_waitcnt lgkmcnt(13)
	v_mfma_f32_32x32x16_bf16 v[68:83], v[166:169], v[122:125], v[68:83]
	ds_read_b64_tr_b16 v[174:175], v183 offset:30720
	ds_read_b64_tr_b16 v[176:177], v183 offset:31232
	v_add_f32_e32 v36, v42, v52
	v_add_f32_e32 v36, v43, v36
	v_add_f32_e32 v36, v44, v36
	v_add_f32_e32 v36, v45, v36
	v_cvt_pk_bf16_f32 v108, v40, v41
	v_cvt_pk_bf16_f32 v109, v42, v43
	s_waitcnt lgkmcnt(14)
	v_mfma_f32_32x32x16_bf16 v[84:99], v[158:161], v[122:125], v[84:99]
	ds_read_b64_tr_b16 v[170:171], v183 offset:27648
	ds_read_b64_tr_b16 v[172:173], v183 offset:28160
	v_add_f32_e32 v36, v46, v36
	v_add_f32_e32 v36, v47, v36
	v_add_f32_e32 v36, v48, v36
	v_add_f32_e32 v36, v49, v36
	v_cvt_pk_bf16_f32 v102, v44, v45
	v_cvt_pk_bf16_f32 v103, v46, v47
	s_waitcnt lgkmcnt(14)
	v_mfma_f32_32x32x16_bf16 v[68:83], v[162:165], v[114:117], v[68:83]
	ds_read_b64_tr_b16 v[166:167], v183 offset:31744
	ds_read_b64_tr_b16 v[168:169], v183 offset:32256
	v_add_f32_e32 v36, v50, v36
	v_add_f32_e32 v36, v51, v36
	v_add_f32_e32 v158, 0, v36
	v_cvt_pk_bf16_f32 v104, v48, v49
	v_cvt_pk_bf16_f32 v105, v50, v51
	v_mfma_f32_32x32x16_bf16 v[84:99], v[154:157], v[114:117], v[84:99]
	v_lshl_add_u64 v[36:37], v[178:179], 0, s[36:37]
	s_add_i32 s8, s4, s57
	s_mov_b32 s9, m0
	s_mov_b32 m0, s8
	s_nop 0
	global_load_lds_dwordx4 v[36:37], off
	s_mov_b32 m0, s9
	v_lshl_add_u64 v[36:37], v[180:181], 0, s[30:31]
	s_add_i32 s8, s60, s58
	s_mov_b32 s9, m0
	s_mov_b32 m0, s8
	s_nop 0
	global_load_lds_dwordx4 v[36:37], off
	s_mov_b32 m0, s9
	v_sub_f32_e32 v52, v68, v211
	s_nop 6
	v_sub_f32_e32 v36, v84, v211
	v_sub_f32_e32 v53, v69, v211
	v_sub_f32_e32 v37, v85, v211
	v_sub_f32_e32 v54, v70, v211
	v_sub_f32_e32 v38, v86, v211
	v_sub_f32_e32 v55, v71, v211
	v_sub_f32_e32 v39, v87, v211
	v_sub_f32_e32 v56, v72, v211
	v_sub_f32_e32 v40, v88, v211
	v_sub_f32_e32 v57, v73, v211
	v_sub_f32_e32 v41, v89, v211
	v_sub_f32_e32 v58, v74, v211
	v_sub_f32_e32 v42, v90, v211
	v_sub_f32_e32 v59, v75, v211
	v_sub_f32_e32 v43, v91, v211
	v_sub_f32_e32 v60, v76, v211
	v_sub_f32_e32 v44, v92, v211
	v_sub_f32_e32 v61, v77, v211
	v_sub_f32_e32 v45, v93, v211
	v_sub_f32_e32 v62, v78, v211
	v_sub_f32_e32 v46, v94, v211
	v_sub_f32_e32 v63, v79, v211
	v_sub_f32_e32 v47, v95, v211
	v_sub_f32_e32 v64, v80, v211
	v_sub_f32_e32 v48, v96, v211
	v_sub_f32_e32 v65, v81, v211
	v_sub_f32_e32 v49, v97, v211
	v_sub_f32_e32 v66, v82, v211
	v_sub_f32_e32 v50, v98, v211
	v_sub_f32_e32 v67, v83, v211
	v_sub_f32_e32 v51, v99, v211
	ds_read_b32 v68, v182 offset:256
	s_waitcnt lgkmcnt(0)
	v_bfe_i32 v69, v68, 0, 1
	v_bfi_b32 v52, v69, s49, v52
	s_nop 0
	v_add_f32_e32 v213, v2, v158
	v_bfe_i32 v69, v68, 1, 1
	v_bfi_b32 v53, v69, s49, v53
	s_nop 0
	s_nop 0
	v_bfe_i32 v69, v68, 2, 1
	v_bfi_b32 v54, v69, s49, v54
	s_nop 0
	s_nop 0
	v_bfe_i32 v69, v68, 3, 1
	v_bfi_b32 v55, v69, s49, v55
	s_nop 0
	s_nop 0
	v_bfe_i32 v69, v68, 4, 1
	v_bfi_b32 v56, v69, s49, v56
	s_nop 0
	s_nop 0
	v_bfe_i32 v69, v68, 5, 1
	v_bfi_b32 v57, v69, s49, v57
	s_nop 0
	s_nop 0
	v_bfe_i32 v69, v68, 6, 1
	v_bfi_b32 v58, v69, s49, v58
	s_nop 0
	s_nop 0
	v_bfe_i32 v69, v68, 7, 1
	v_bfi_b32 v59, v69, s49, v59
	s_nop 0
	s_nop 0
	v_bfe_i32 v69, v68, 8, 1
	v_bfi_b32 v60, v69, s49, v60
	s_nop 0
	s_nop 0
	v_bfe_i32 v69, v68, 9, 1
	v_bfi_b32 v61, v69, s49, v61
	s_nop 0
	s_nop 0
	v_bfe_i32 v69, v68, 10, 1
	v_bfi_b32 v62, v69, s49, v62
	s_nop 0
	s_nop 0
	v_bfe_i32 v69, v68, 11, 1
	v_bfi_b32 v63, v69, s49, v63
	s_nop 0
	s_nop 0
	v_bfe_i32 v69, v68, 12, 1
	v_bfi_b32 v64, v69, s49, v64
	s_nop 0
	s_nop 0
	v_bfe_i32 v69, v68, 13, 1
	v_bfi_b32 v65, v69, s49, v65
	s_nop 0
	s_nop 0
	v_bfe_i32 v69, v68, 14, 1
	v_bfi_b32 v66, v69, s49, v66
	s_nop 0
	s_nop 0
	v_bfe_i32 v69, v68, 15, 1
	v_bfi_b32 v67, v69, s49, v67
	s_nop 0
	s_nop 0
	v_bfe_i32 v69, v68, 16, 1
	v_bfi_b32 v36, v69, s49, v36
	s_nop 0
	s_nop 0
	v_bfe_i32 v69, v68, 17, 1
	v_bfi_b32 v37, v69, s49, v37
	s_nop 0
	s_nop 0
	v_bfe_i32 v69, v68, 18, 1
	v_bfi_b32 v38, v69, s49, v38
	s_nop 0
	s_nop 0
	v_bfe_i32 v69, v68, 19, 1
	v_bfi_b32 v39, v69, s49, v39
	s_nop 0
	s_nop 0
	v_bfe_i32 v69, v68, 20, 1
	v_bfi_b32 v40, v69, s49, v40
	s_nop 0
	s_nop 0
	v_bfe_i32 v69, v68, 21, 1
	v_bfi_b32 v41, v69, s49, v41
	s_nop 0
	s_nop 0
	v_bfe_i32 v69, v68, 22, 1
	v_bfi_b32 v42, v69, s49, v42
	s_nop 0
	s_nop 0
	v_bfe_i32 v69, v68, 23, 1
	v_bfi_b32 v43, v69, s49, v43
	s_nop 0
	s_nop 0
	v_bfe_i32 v69, v68, 24, 1
	v_bfi_b32 v44, v69, s49, v44
	s_nop 0
	s_nop 0
	v_bfe_i32 v69, v68, 25, 1
	v_bfi_b32 v45, v69, s49, v45
	s_nop 0
	s_nop 0
	v_bfe_i32 v69, v68, 26, 1
	v_bfi_b32 v46, v69, s49, v46
	s_nop 0
	s_nop 0
	v_bfe_i32 v69, v68, 27, 1
	v_bfi_b32 v47, v69, s49, v47
	s_nop 0
	s_nop 0
	v_bfe_i32 v69, v68, 28, 1
	v_bfi_b32 v48, v69, s49, v48
	s_nop 0
	s_nop 0
	v_bfe_i32 v69, v68, 29, 1
	v_bfi_b32 v49, v69, s49, v49
	s_nop 0
	s_nop 0
	v_bfe_i32 v69, v68, 30, 1
	v_bfi_b32 v50, v69, s49, v50
	s_nop 0
	s_nop 0
	v_bfe_i32 v69, v68, 31, 1
	v_bfi_b32 v51, v69, s49, v51
	s_nop 0
	v_max_f32_e32 v68, v53, v53
	v_max_f32_e32 v69, v52, v52
	v_max_f32_e32 v68, v69, v68
	v_max3_f32 v69, v54, v55, v37
	v_max3_f32 v68, v68, v36, v38
	v_max3_f32 v68, v68, v39, v56
	v_max3_f32 v69, v69, v58, v59
	v_max3_f32 v68, v68, v57, v40
	v_max3_f32 v69, v69, v42, v43
	v_max3_f32 v68, v68, v41, v60
	v_max3_f32 v69, v69, v62, v63
	v_max3_f32 v68, v68, v61, v44
	v_max3_f32 v69, v69, v46, v47
	v_max3_f32 v68, v68, v45, v64
	v_max3_f32 v69, v69, v66, v67
	v_max3_f32 v68, v68, v65, v48
	v_max3_f32 v69, v69, v50, v51
	v_max3_f32 v2, v68, v49, v69
	v_mov_b32_e32 v68, v2
	s_nop 1
	v_permlane32_swap_b32_e32 v2, v68
	v_max_f32_e32 v68, v68, v68
	v_max_f32_e32 v2, v2, v2
	v_max_f32_e32 v2, v2, v68
	v_cmp_lt_f32_e32 vcc, s51, v2
	s_cmp_lg_u64 vcc, 0
	s_cselect_b64 s[8:9], -1, 0
	s_cbranch_vccnz .LBB0_1913

.LBB0_1920:
	v_lshl_add_u64 v[224:225], v[222:223], 0, s[8:9]
	v_add_f32_e32 v213, v213, v36
	v_lshl_add_u64 v[36:37], v[224:225], 0, s[26:27]
	s_add_i32 s2, s62, s58
	s_mov_b32 s3, m0
	s_mov_b32 m0, s2
	s_nop 0
	global_load_lds_dwordx4 v[36:37], off
	s_mov_b32 m0, s3
	v_add_u32_e32 v50, 0xffffff00, v2
	v_sub_f32_e32 v52, v68, v211
	v_sub_f32_e32 v36, v84, v211
	v_sub_f32_e32 v53, v69, v211
	v_sub_f32_e32 v37, v85, v211
	v_sub_f32_e32 v54, v70, v211
	v_sub_f32_e32 v38, v86, v211
	v_sub_f32_e32 v55, v71, v211
	v_sub_f32_e32 v39, v87, v211
	v_sub_f32_e32 v56, v72, v211
	v_sub_f32_e32 v40, v88, v211
	v_sub_f32_e32 v57, v73, v211
	v_sub_f32_e32 v41, v89, v211
	v_sub_f32_e32 v58, v74, v211
	v_sub_f32_e32 v42, v90, v211
	v_sub_f32_e32 v59, v75, v211
	v_sub_f32_e32 v43, v91, v211
	v_sub_f32_e32 v60, v76, v211
	v_sub_f32_e32 v44, v92, v211
	v_sub_f32_e32 v61, v77, v211
	v_sub_f32_e32 v45, v93, v211
	v_sub_f32_e32 v62, v78, v211
	v_sub_f32_e32 v46, v94, v211
	v_sub_f32_e32 v63, v79, v211
	v_sub_f32_e32 v47, v95, v211
	v_sub_f32_e32 v64, v80, v211
	v_sub_f32_e32 v48, v96, v211
	v_sub_f32_e32 v65, v81, v211
	v_sub_f32_e32 v49, v97, v211
	ds_read_b32 v68, v50
	v_sub_f32_e32 v66, v82, v211
	v_sub_f32_e32 v50, v98, v211
	v_sub_f32_e32 v67, v83, v211
	v_sub_f32_e32 v51, v99, v211
	s_waitcnt lgkmcnt(0)
	v_bfe_i32 v69, v68, 0, 1
	v_bfi_b32 v52, v69, s49, v52
	s_nop 0
	s_nop 0
	v_bfe_i32 v69, v68, 1, 1
	v_bfi_b32 v53, v69, s49, v53
	s_nop 0
	s_nop 0
	v_bfe_i32 v69, v68, 2, 1
	v_bfi_b32 v54, v69, s49, v54
	s_nop 0
	s_nop 0
	v_bfe_i32 v69, v68, 3, 1
	v_bfi_b32 v55, v69, s49, v55
	s_nop 0
	s_nop 0
	v_bfe_i32 v69, v68, 4, 1
	v_bfi_b32 v56, v69, s49, v56
	s_nop 0
	s_nop 0
	v_bfe_i32 v69, v68, 5, 1
	v_bfi_b32 v57, v69, s49, v57
	s_nop 0
	s_nop 0
	v_bfe_i32 v69, v68, 6, 1
	v_bfi_b32 v58, v69, s49, v58
	s_nop 0
	s_nop 0
	v_bfe_i32 v69, v68, 7, 1
	v_bfi_b32 v59, v69, s49, v59
	s_nop 0
	s_nop 0
	v_bfe_i32 v69, v68, 8, 1
	v_bfi_b32 v60, v69, s49, v60
	s_nop 0
	s_nop 0
	v_bfe_i32 v69, v68, 9, 1
	v_bfi_b32 v61, v69, s49, v61
	s_nop 0
	s_nop 0
	v_bfe_i32 v69, v68, 10, 1
	v_bfi_b32 v62, v69, s49, v62
	s_nop 0
	s_nop 0
	v_bfe_i32 v69, v68, 11, 1
	v_bfi_b32 v63, v69, s49, v63
	s_nop 0
	s_nop 0
	v_bfe_i32 v69, v68, 12, 1
	v_bfi_b32 v64, v69, s49, v64
	s_nop 0
	s_nop 0
	v_bfe_i32 v69, v68, 13, 1
	v_bfi_b32 v65, v69, s49, v65
	s_nop 0
	s_nop 0
	v_bfe_i32 v69, v68, 14, 1
	v_bfi_b32 v66, v69, s49, v66
	s_nop 0
	s_nop 0
	v_bfe_i32 v69, v68, 15, 1
	v_bfi_b32 v67, v69, s49, v67
	s_nop 0
	s_nop 0
	v_bfe_i32 v69, v68, 16, 1
	v_bfi_b32 v36, v69, s49, v36
	s_nop 0
	s_nop 0
	v_bfe_i32 v69, v68, 17, 1
	v_bfi_b32 v37, v69, s49, v37
	s_nop 0
	s_nop 0
	v_bfe_i32 v69, v68, 18, 1
	v_bfi_b32 v38, v69, s49, v38
	s_nop 0
	s_nop 0
	v_bfe_i32 v69, v68, 19, 1
	v_bfi_b32 v39, v69, s49, v39
	s_nop 0
	s_nop 0
	v_bfe_i32 v69, v68, 20, 1
	v_bfi_b32 v40, v69, s49, v40
	s_nop 0
	s_nop 0
	v_bfe_i32 v69, v68, 21, 1
	v_bfi_b32 v41, v69, s49, v41
	s_nop 0
	s_nop 0
	v_bfe_i32 v69, v68, 22, 1
	v_bfi_b32 v42, v69, s49, v42
	s_nop 0
	s_nop 0
	v_bfe_i32 v69, v68, 23, 1
	v_bfi_b32 v43, v69, s49, v43
	s_nop 0
	s_nop 0
	v_bfe_i32 v69, v68, 24, 1
	v_bfi_b32 v44, v69, s49, v44
	s_nop 0
	s_nop 0
	v_bfe_i32 v69, v68, 25, 1
	v_bfi_b32 v45, v69, s49, v45
	s_nop 0
	s_nop 0
	v_bfe_i32 v69, v68, 26, 1
	v_bfi_b32 v46, v69, s49, v46
	s_nop 0
	s_nop 0
	v_bfe_i32 v69, v68, 27, 1
	v_bfi_b32 v47, v69, s49, v47
	s_nop 0
	s_nop 0
	v_bfe_i32 v69, v68, 28, 1
	v_bfi_b32 v48, v69, s49, v48
	s_nop 0
	s_nop 0
	v_bfe_i32 v69, v68, 29, 1
	v_bfi_b32 v49, v69, s49, v49
	s_nop 0
	s_nop 0
	v_bfe_i32 v69, v68, 30, 1
	v_bfi_b32 v50, v69, s49, v50
	s_nop 0
	s_nop 0
	v_bfe_i32 v69, v68, 31, 1
	v_bfi_b32 v51, v69, s49, v51
	s_nop 0
	v_max_f32_e32 v68, v53, v53
	v_max_f32_e32 v69, v52, v52
	v_max_f32_e32 v68, v69, v68
	v_max3_f32 v69, v54, v55, v37
	v_max3_f32 v68, v68, v36, v38
	v_max3_f32 v68, v68, v39, v56
	v_max3_f32 v69, v69, v58, v59
	v_max3_f32 v68, v68, v57, v40
	v_max3_f32 v69, v69, v42, v43
	v_max3_f32 v68, v68, v41, v60
	v_max3_f32 v69, v69, v62, v63
	v_max3_f32 v68, v68, v61, v44
	v_max3_f32 v69, v69, v46, v47
	v_max3_f32 v68, v68, v45, v64
	v_max3_f32 v69, v69, v66, v67
	v_max3_f32 v68, v68, v65, v48
	v_max3_f32 v69, v69, v50, v51
	v_max3_f32 v68, v68, v49, v69
	v_mov_b32_e32 v69, v68
	s_nop 1
	v_permlane32_swap_b32_e32 v68, v69
	v_max_f32_e32 v69, v69, v69
	v_max_f32_e32 v68, v68, v68
	v_max_f32_e32 v68, v68, v69
	v_cmp_lt_f32_e32 vcc, s51, v68
	s_cmp_lg_u64 vcc, 0
	s_cselect_b64 s[2:3], -1, 0
	s_cbranch_vccnz .LBB0_1956

.LBB0_1933:
	v_add_f32_e32 v213, v213, v36
	v_sub_f32_e32 v52, v68, v211
	v_sub_f32_e32 v36, v84, v211
	v_sub_f32_e32 v53, v69, v211
	v_sub_f32_e32 v37, v85, v211
	v_sub_f32_e32 v54, v70, v211
	v_sub_f32_e32 v38, v86, v211
	v_sub_f32_e32 v55, v71, v211
	v_sub_f32_e32 v39, v87, v211
	v_sub_f32_e32 v56, v72, v211
	v_sub_f32_e32 v40, v88, v211
	v_sub_f32_e32 v57, v73, v211
	v_sub_f32_e32 v41, v89, v211
	v_sub_f32_e32 v58, v74, v211
	v_sub_f32_e32 v42, v90, v211
	v_sub_f32_e32 v59, v75, v211
	v_sub_f32_e32 v43, v91, v211
	v_sub_f32_e32 v60, v76, v211
	v_sub_f32_e32 v44, v92, v211
	v_sub_f32_e32 v61, v77, v211
	v_sub_f32_e32 v45, v93, v211
	v_sub_f32_e32 v62, v78, v211
	v_sub_f32_e32 v46, v94, v211
	v_sub_f32_e32 v63, v79, v211
	v_sub_f32_e32 v47, v95, v211
	v_sub_f32_e32 v64, v80, v211
	v_sub_f32_e32 v48, v96, v211
	v_sub_f32_e32 v65, v81, v211
	v_sub_f32_e32 v49, v97, v211
	v_sub_f32_e32 v66, v82, v211
	v_sub_f32_e32 v50, v98, v211
	v_sub_f32_e32 v67, v83, v211
	v_sub_f32_e32 v51, v99, v211
	ds_read_b32 v68, v2
	s_waitcnt lgkmcnt(0)
	v_bfe_i32 v69, v68, 0, 1
	v_bfi_b32 v52, v69, s49, v52
	s_nop 0
	s_nop 0
	v_bfe_i32 v69, v68, 1, 1
	v_bfi_b32 v53, v69, s49, v53
	s_nop 0
	s_nop 0
	v_bfe_i32 v69, v68, 2, 1
	v_bfi_b32 v54, v69, s49, v54
	s_nop 0
	s_nop 0
	v_bfe_i32 v69, v68, 3, 1
	v_bfi_b32 v55, v69, s49, v55
	s_nop 0
	s_nop 0
	v_bfe_i32 v69, v68, 4, 1
	v_bfi_b32 v56, v69, s49, v56
	s_nop 0
	s_nop 0
	v_bfe_i32 v69, v68, 5, 1
	v_bfi_b32 v57, v69, s49, v57
	s_nop 0
	s_nop 0
	v_bfe_i32 v69, v68, 6, 1
	v_bfi_b32 v58, v69, s49, v58
	s_nop 0
	s_nop 0
	v_bfe_i32 v69, v68, 7, 1
	v_bfi_b32 v59, v69, s49, v59
	s_nop 0
	s_nop 0
	v_bfe_i32 v69, v68, 8, 1
	v_bfi_b32 v60, v69, s49, v60
	s_nop 0
	s_nop 0
	v_bfe_i32 v69, v68, 9, 1
	v_bfi_b32 v61, v69, s49, v61
	s_nop 0
	s_nop 0
	v_bfe_i32 v69, v68, 10, 1
	v_bfi_b32 v62, v69, s49, v62
	s_nop 0
	s_nop 0
	v_bfe_i32 v69, v68, 11, 1
	v_bfi_b32 v63, v69, s49, v63
	s_nop 0
	s_nop 0
	v_bfe_i32 v69, v68, 12, 1
	v_bfi_b32 v64, v69, s49, v64
	s_nop 0
	s_nop 0
	v_bfe_i32 v69, v68, 13, 1
	v_bfi_b32 v65, v69, s49, v65
	s_nop 0
	s_nop 0
	v_bfe_i32 v69, v68, 14, 1
	v_bfi_b32 v66, v69, s49, v66
	s_nop 0
	s_nop 0
	v_bfe_i32 v69, v68, 15, 1
	v_bfi_b32 v67, v69, s49, v67
	s_nop 0
	s_nop 0
	v_bfe_i32 v69, v68, 16, 1
	v_bfi_b32 v36, v69, s49, v36
	s_nop 0
	s_nop 0
	v_bfe_i32 v69, v68, 17, 1
	v_bfi_b32 v37, v69, s49, v37
	s_nop 0
	s_nop 0
	v_bfe_i32 v69, v68, 18, 1
	v_bfi_b32 v38, v69, s49, v38
	s_nop 0
	s_nop 0
	v_bfe_i32 v69, v68, 19, 1
	v_bfi_b32 v39, v69, s49, v39
	s_nop 0
	s_nop 0
	v_bfe_i32 v69, v68, 20, 1
	v_bfi_b32 v40, v69, s49, v40
	s_nop 0
	s_nop 0
	v_bfe_i32 v69, v68, 21, 1
	v_bfi_b32 v41, v69, s49, v41
	s_nop 0
	s_nop 0
	v_bfe_i32 v69, v68, 22, 1
	v_bfi_b32 v42, v69, s49, v42
	s_nop 0
	s_nop 0
	v_bfe_i32 v69, v68, 23, 1
	v_bfi_b32 v43, v69, s49, v43
	s_nop 0
	s_nop 0
	v_bfe_i32 v69, v68, 24, 1
	v_bfi_b32 v44, v69, s49, v44
	s_nop 0
	s_nop 0
	v_bfe_i32 v69, v68, 25, 1
	v_bfi_b32 v45, v69, s49, v45
	s_nop 0
	s_nop 0
	v_bfe_i32 v69, v68, 26, 1
	v_bfi_b32 v46, v69, s49, v46
	s_nop 0
	s_nop 0
	v_bfe_i32 v69, v68, 27, 1
	v_bfi_b32 v47, v69, s49, v47
	s_nop 0
	s_nop 0
	v_bfe_i32 v69, v68, 28, 1
	v_bfi_b32 v48, v69, s49, v48
	s_nop 0
	s_nop 0
	v_bfe_i32 v69, v68, 29, 1
	v_bfi_b32 v49, v69, s49, v49
	s_nop 0
	s_nop 0
	v_bfe_i32 v69, v68, 30, 1
	v_bfi_b32 v50, v69, s49, v50
	s_nop 0
	s_nop 0
	v_bfe_i32 v69, v68, 31, 1
	v_bfi_b32 v51, v69, s49, v51
	s_nop 0
	v_max_f32_e32 v68, v53, v53
	v_max_f32_e32 v69, v52, v52
	v_max_f32_e32 v68, v69, v68
	v_max3_f32 v69, v54, v55, v37
	v_max3_f32 v68, v68, v36, v38
	v_max3_f32 v68, v68, v39, v56
	v_max3_f32 v69, v69, v58, v59
	v_max3_f32 v68, v68, v57, v40
	v_max3_f32 v69, v69, v42, v43
	v_max3_f32 v68, v68, v41, v60
	v_max3_f32 v69, v69, v62, v63
	v_max3_f32 v68, v68, v61, v44
	v_max3_f32 v69, v69, v46, v47
	v_max3_f32 v68, v68, v45, v64
	v_max3_f32 v69, v69, v66, v67
	v_max3_f32 v68, v68, v65, v48
	v_max3_f32 v69, v69, v50, v51
	v_max3_f32 v68, v68, v49, v69
	v_mov_b32_e32 v69, v68
	s_nop 1
	v_permlane32_swap_b32_e32 v68, v69
	v_max_f32_e32 v69, v69, v69
	v_max_f32_e32 v68, v68, v68
	v_max_f32_e32 v68, v68, v69
	v_cmp_lt_f32_e32 vcc, s51, v68
	s_cmp_lg_u64 vcc, 0
	s_cselect_b64 s[12:13], -1, 0
	s_cbranch_vccnz .LBB0_1959

.LBB0_1964:
	v_add_u32_e32 v2, s62, v199
	ds_read_b64_tr_b16 v[166:167], v2 offset:24576
	ds_read_b64_tr_b16 v[168:169], v2 offset:25088
	v_add_f32_e32 v68, v52, v53
	v_add_f32_e32 v68, v54, v68
	v_add_f32_e32 v68, v55, v68
	v_add_f32_e32 v68, v56, v68
	v_add_f32_e32 v84, v57, v68
	s_waitcnt lgkmcnt(3)
	v_mfma_f32_32x32x16_bf16 v[68:83], v[162:165], v[130:133], 0
	v_cvt_pk_bf16_f32 v118, v52, v53
	v_cvt_pk_bf16_f32 v119, v54, v55
	ds_read_b64_tr_b16 v[162:163], v2 offset:28672
	ds_read_b64_tr_b16 v[164:165], v2 offset:29184
	v_add_f32_e32 v52, v58, v84
	v_add_f32_e32 v52, v59, v52
	v_add_f32_e32 v52, v60, v52
	v_add_f32_e32 v52, v61, v52
	v_cvt_pk_bf16_f32 v120, v56, v57
	v_cvt_pk_bf16_f32 v121, v58, v59
	s_waitcnt lgkmcnt(4)
	v_mfma_f32_32x32x16_bf16 v[84:99], v[158:161], v[130:133], 0
	ds_read_b64_tr_b16 v[158:159], v2 offset:25600
	ds_read_b64_tr_b16 v[160:161], v2 offset:26112
	v_mfma_f32_32x32x16_bf16 v[68:83], v[154:157], v[126:129], v[68:83]
	v_add_f32_e32 v52, v62, v52
	v_add_f32_e32 v52, v63, v52
	v_add_f32_e32 v52, v64, v52
	v_add_f32_e32 v52, v65, v52
	v_cvt_pk_bf16_f32 v110, v60, v61
	v_cvt_pk_bf16_f32 v111, v62, v63
	ds_read_b64_tr_b16 v[154:155], v2 offset:29696
	ds_read_b64_tr_b16 v[156:157], v2 offset:30208
	v_add_f32_e32 v52, v66, v52
	v_add_f32_e32 v52, v67, v52
	v_add_f32_e32 v52, v36, v52
	v_add_f32_e32 v52, v37, v52
	v_cvt_pk_bf16_f32 v112, v64, v65
	v_cvt_pk_bf16_f32 v113, v66, v67
	v_mfma_f32_32x32x16_bf16 v[84:99], v[150:153], v[126:129], v[84:99]
	ds_read_b64_tr_b16 v[150:151], v2 offset:26624
	ds_read_b64_tr_b16 v[152:153], v2 offset:27136
	v_mfma_f32_32x32x16_bf16 v[68:83], v[146:149], v[122:125], v[68:83]
	v_add_f32_e32 v52, v38, v52
	v_add_f32_e32 v52, v39, v52
	v_add_f32_e32 v52, v40, v52
	v_add_f32_e32 v52, v41, v52
	v_cvt_pk_bf16_f32 v106, v36, v37
	v_cvt_pk_bf16_f32 v107, v38, v39
	ds_read_b64_tr_b16 v[130:131], v2 offset:30720
	ds_read_b64_tr_b16 v[132:133], v2 offset:31232
	v_add_f32_e32 v36, v42, v52
	v_add_f32_e32 v36, v43, v36
	v_add_f32_e32 v36, v44, v36
	v_add_f32_e32 v36, v45, v36
	v_cvt_pk_bf16_f32 v108, v40, v41
	v_cvt_pk_bf16_f32 v109, v42, v43
	v_mfma_f32_32x32x16_bf16 v[84:99], v[142:145], v[122:125], v[84:99]
	ds_read_b64_tr_b16 v[126:127], v2 offset:27648
	ds_read_b64_tr_b16 v[128:129], v2 offset:28160
	v_mfma_f32_32x32x16_bf16 v[68:83], v[138:141], v[114:117], v[68:83]
	v_add_f32_e32 v36, v46, v36
	v_add_f32_e32 v36, v47, v36
	v_add_f32_e32 v36, v48, v36
	v_add_f32_e32 v36, v49, v36
	v_cvt_pk_bf16_f32 v102, v44, v45
	v_cvt_pk_bf16_f32 v103, v46, v47
	ds_read_b64_tr_b16 v[122:123], v2 offset:31744
	ds_read_b64_tr_b16 v[124:125], v2 offset:32256
	v_add_f32_e32 v2, v50, v36
	v_add_f32_e32 v2, v51, v2
	v_add_f32_e32 v2, 0, v2
	v_cvt_pk_bf16_f32 v104, v48, v49
	v_cvt_pk_bf16_f32 v105, v50, v51
	v_mfma_f32_32x32x16_bf16 v[84:99], v[134:137], v[114:117], v[84:99]
	v_lshl_add_u32 v50, s56, 2, v209
	v_sub_f32_e32 v52, v68, v211
	s_nop 9
	v_sub_f32_e32 v36, v84, v211
	v_sub_f32_e32 v53, v69, v211
	v_sub_f32_e32 v37, v85, v211
	v_sub_f32_e32 v54, v70, v211
	v_sub_f32_e32 v38, v86, v211
	v_sub_f32_e32 v55, v71, v211
	v_sub_f32_e32 v39, v87, v211
	v_sub_f32_e32 v56, v72, v211
	v_sub_f32_e32 v40, v88, v211
	v_sub_f32_e32 v57, v73, v211
	v_sub_f32_e32 v41, v89, v211
	v_sub_f32_e32 v58, v74, v211
	v_sub_f32_e32 v42, v90, v211
	v_sub_f32_e32 v59, v75, v211
	v_sub_f32_e32 v43, v91, v211
	v_sub_f32_e32 v60, v76, v211
	v_sub_f32_e32 v44, v92, v211
	v_sub_f32_e32 v61, v77, v211
	v_sub_f32_e32 v45, v93, v211
	v_sub_f32_e32 v62, v78, v211
	v_sub_f32_e32 v46, v94, v211
	v_sub_f32_e32 v63, v79, v211
	v_sub_f32_e32 v47, v95, v211
	v_sub_f32_e32 v64, v80, v211
	v_sub_f32_e32 v48, v96, v211
	v_sub_f32_e32 v65, v81, v211
	v_sub_f32_e32 v49, v97, v211
	ds_read_b32 v68, v50 offset:768
	v_sub_f32_e32 v66, v82, v211
	v_sub_f32_e32 v50, v98, v211
	v_sub_f32_e32 v67, v83, v211
	v_sub_f32_e32 v51, v99, v211
	s_waitcnt lgkmcnt(0)
	v_bfe_i32 v69, v68, 0, 1
	v_bfi_b32 v52, v69, s49, v52
	s_nop 0
	v_add_f32_e32 v2, v213, v2
	v_bfe_i32 v69, v68, 1, 1
	v_bfi_b32 v53, v69, s49, v53
	s_nop 0
	s_nop 0
	v_bfe_i32 v69, v68, 2, 1
	v_bfi_b32 v54, v69, s49, v54
	s_nop 0
	s_nop 0
	v_bfe_i32 v69, v68, 3, 1
	v_bfi_b32 v55, v69, s49, v55
	s_nop 0
	s_nop 0
	v_bfe_i32 v69, v68, 4, 1
	v_bfi_b32 v56, v69, s49, v56
	s_nop 0
	s_nop 0
	v_bfe_i32 v69, v68, 5, 1
	v_bfi_b32 v57, v69, s49, v57
	s_nop 0
	s_nop 0
	v_bfe_i32 v69, v68, 6, 1
	v_bfi_b32 v58, v69, s49, v58
	s_nop 0
	s_nop 0
	v_bfe_i32 v69, v68, 7, 1
	v_bfi_b32 v59, v69, s49, v59
	s_nop 0
	s_nop 0
	v_bfe_i32 v69, v68, 8, 1
	v_bfi_b32 v60, v69, s49, v60
	s_nop 0
	s_nop 0
	v_bfe_i32 v69, v68, 9, 1
	v_bfi_b32 v61, v69, s49, v61
	s_nop 0
	s_nop 0
	v_bfe_i32 v69, v68, 10, 1
	v_bfi_b32 v62, v69, s49, v62
	s_nop 0
	s_nop 0
	v_bfe_i32 v69, v68, 11, 1
	v_bfi_b32 v63, v69, s49, v63
	s_nop 0
	s_nop 0
	v_bfe_i32 v69, v68, 12, 1
	v_bfi_b32 v64, v69, s49, v64
	s_nop 0
	s_nop 0
	v_bfe_i32 v69, v68, 13, 1
	v_bfi_b32 v65, v69, s49, v65
	s_nop 0
	s_nop 0
	v_bfe_i32 v69, v68, 14, 1
	v_bfi_b32 v66, v69, s49, v66
	s_nop 0
	s_nop 0
	v_bfe_i32 v69, v68, 15, 1
	v_bfi_b32 v67, v69, s49, v67
	s_nop 0
	s_nop 0
	v_bfe_i32 v69, v68, 16, 1
	v_bfi_b32 v36, v69, s49, v36
	s_nop 0
	s_nop 0
	v_bfe_i32 v69, v68, 17, 1
	v_bfi_b32 v37, v69, s49, v37
	s_nop 0
	s_nop 0
	v_bfe_i32 v69, v68, 18, 1
	v_bfi_b32 v38, v69, s49, v38
	s_nop 0
	s_nop 0
	v_bfe_i32 v69, v68, 19, 1
	v_bfi_b32 v39, v69, s49, v39
	s_nop 0
	s_nop 0
	v_bfe_i32 v69, v68, 20, 1
	v_bfi_b32 v40, v69, s49, v40
	s_nop 0
	s_nop 0
	v_bfe_i32 v69, v68, 21, 1
	v_bfi_b32 v41, v69, s49, v41
	s_nop 0
	s_nop 0
	v_bfe_i32 v69, v68, 22, 1
	v_bfi_b32 v42, v69, s49, v42
	s_nop 0
	s_nop 0
	v_bfe_i32 v69, v68, 23, 1
	v_bfi_b32 v43, v69, s49, v43
	s_nop 0
	s_nop 0
	v_bfe_i32 v69, v68, 24, 1
	v_bfi_b32 v44, v69, s49, v44
	s_nop 0
	s_nop 0
	v_bfe_i32 v69, v68, 25, 1
	v_bfi_b32 v45, v69, s49, v45
	s_nop 0
	s_nop 0
	v_bfe_i32 v69, v68, 26, 1
	v_bfi_b32 v46, v69, s49, v46
	s_nop 0
	s_nop 0
	v_bfe_i32 v69, v68, 27, 1
	v_bfi_b32 v47, v69, s49, v47
	s_nop 0
	s_nop 0
	v_bfe_i32 v69, v68, 28, 1
	v_bfi_b32 v48, v69, s49, v48
	s_nop 0
	s_nop 0
	v_bfe_i32 v69, v68, 29, 1
	v_bfi_b32 v49, v69, s49, v49
	s_nop 0
	s_nop 0
	v_bfe_i32 v69, v68, 30, 1
	v_bfi_b32 v50, v69, s49, v50
	s_nop 0
	s_nop 0
	v_bfe_i32 v69, v68, 31, 1
	v_bfi_b32 v51, v69, s49, v51
	s_nop 0
	v_max_f32_e32 v68, v53, v53
	v_max_f32_e32 v69, v52, v52
	v_max_f32_e32 v68, v69, v68
	v_max3_f32 v69, v54, v55, v37
	v_max3_f32 v68, v68, v36, v38
	v_max3_f32 v68, v68, v39, v56
	v_max3_f32 v69, v69, v58, v59
	v_max3_f32 v68, v68, v57, v40
	v_max3_f32 v69, v69, v42, v43
	v_max3_f32 v68, v68, v41, v60
	v_max3_f32 v69, v69, v62, v63
	v_max3_f32 v68, v68, v61, v44
	v_max3_f32 v69, v69, v46, v47
	v_max3_f32 v68, v68, v45, v64
	v_max3_f32 v69, v69, v66, v67
	v_max3_f32 v68, v68, v65, v48
	v_max3_f32 v69, v69, v50, v51
	v_max3_f32 v68, v68, v49, v69
	v_mov_b32_e32 v69, v68
	s_nop 1
	v_permlane32_swap_b32_e32 v68, v69
	v_max_f32_e32 v69, v69, v69
	v_max_f32_e32 v68, v68, v68
	v_max_f32_e32 v68, v68, v69
	v_cmp_lt_f32_e32 vcc, s51, v68
	s_cmp_lg_u64 vcc, 0
	s_cselect_b64 s[2:3], -1, 0
	s_cbranch_vccnz .LBB0_1969
